# scan step loop: y-reduction hazard slots carry the next half step's first LDS reads; 4-byte instructions paired so 8-byte ones stay aligned; loop heads 128B-aligned; retention placement pinned
# speedup vs baseline: 1.0016x; 1.0016x over previous
; DI int ltid() { int t = __builtin_amdgcn_workitem_id_x(); asm volatile("" : "+v"(t)); return t; }
; DI void scan_item(const Params& p, int l, bool ctx_out, int item, char* smem) {
;   const int dir = item & 1, h = (item >> 1) & 7, b = item >> 4;
;   const int tid = ltid(), lane = tid & 63, w = tid >> 6;
;   const int c = lane, tg = w;
;   const int kg = lane & 15, rg = lane >> 4;
;   const u16* __restrict__ Z = (const u16*)(p.ws + OFF_ZRW);
;   u16* YD = (u16*)(p.ws + OFF_QK) + (size_t)dir * NT * 512;
;   float* BON = (float*)(p.ws + OFF_BONUS) + (size_t)dir * NT * 8;
;   float* zs = (float*)smem;
;   float* ops = zs + TC * 3 * 64;
;   u16* zwb = (u16*)(ops + TC * 4 * 64);
;   u16* zab = zwb + 16 * 72;
;   const int hc = h * 64 + c;
;   const int cl = lane & 15, q4 = lane >> 4;
;   bf16x8 bw[2], ba[2];
;   {
;     const float* w2 = p.rwkv_w2 + (size_t)(l * 2 + dir) * 64 * 512 + h * 64 + 16 * w + cl;
;     const float* a2 = p.rwkv_a2 + (size_t)(l * 2 + dir) * 64 * 512 + h * 64 + 16 * w + cl;
; #pragma unroll
;     for (int s = 0; s < 2; ++s)
; #pragma unroll
;       for (int jj = 0; jj < 8; ++jj) {
;         const int j = s * 32 + q4 * 8 + jj;
;         bw[s][jj] = (short)f2bf(w2[j * 512]);
;         ba[s][jj] = (short)f2bf(a2[j * 512]);
;       }
;   }
;   const int hc2 = h * 64 + 16 * w + cl;
;   const float w0c = p.rwkv_w0[(l * 2 + dir) * 512 + hc2], a0c = p.rwkv_a0[(l * 2 + dir) * 512 + hc2];
;   const float kac = p.rwkv_k_a[l * 512 + hc2];
;   const float kkc = p.rwkv_k_k[l * 512 + hc];
;   f32x4 rk4;
; #pragma unroll
;   for (int j = 0; j < 4; ++j) rk4[j] = 0.5f * p.rwkv_r_k[l * 512 + h * 64 + 4 * kg + j];
;   const int gcol[5] = {hc, 512 + hc, 1024 + hc, 1536 + 64 * dir + c, 1664 + 64 * dir + c};
;   float muv[5];
; #pragma unroll
;   for (int g = 0; g < 5; ++g) muv[g] = p.rwkv_mu[l * RWB + gcol[g]];
;   float S[4][4];
; #pragma unroll
;   for (int a = 0; a < 4; ++a)
; #pragma unroll
;     for (int j = 0; j < 4; ++j) S[a][j] = 0.f;
;   __syncthreads();
;   u16 raw[4][5][2];
;   const int NCH = 256 / TC + 2048 / TC;
.LBB0_196:
	s_andn2_b64 vcc, exec, s[0:1]
	s_cbranch_vccnz .LBB0_463
	v_readlane_b32 s0, v246, 27
	v_readlane_b32 s1, v246, 28
	s_andn2_b64 vcc, exec, s[0:1]
	s_cbranch_vccnz .LBB0_463
	.p2alignl 7, 3212836864
	s_nop 0
	s_nop 0
	s_nop 0
	v_writelane_b32 v255, s0, 0
	v_writelane_b32 v255, s1, 1
	v_writelane_b32 v255, s2, 2
	v_writelane_b32 v255, s3, 3
	v_writelane_b32 v255, s4, 4
	v_writelane_b32 v255, s5, 5
	v_writelane_b32 v255, s6, 6
	v_writelane_b32 v255, s7, 7
	v_writelane_b32 v255, s8, 8
	v_writelane_b32 v255, s9, 9
	v_writelane_b32 v255, s10, 10
	v_writelane_b32 v255, s11, 11
	v_writelane_b32 v255, s12, 12
	v_writelane_b32 v255, s13, 13
	v_writelane_b32 v255, s14, 14
	v_writelane_b32 v255, s15, 15
	v_writelane_b32 v255, s16, 16
	v_writelane_b32 v255, s17, 17
	v_writelane_b32 v255, s18, 18
	v_writelane_b32 v255, s19, 19
	v_writelane_b32 v255, s20, 20
	v_writelane_b32 v255, s21, 21
	v_writelane_b32 v255, s22, 22
	v_writelane_b32 v255, s23, 23
	v_writelane_b32 v255, s24, 24
	v_writelane_b32 v255, s25, 25
	v_writelane_b32 v255, s26, 26
	v_writelane_b32 v255, s27, 27
	v_writelane_b32 v255, s28, 28
	v_writelane_b32 v255, s29, 29
	v_writelane_b32 v255, s30, 30
	v_writelane_b32 v255, s31, 31
	v_writelane_b32 v255, s32, 32
	v_writelane_b32 v255, s33, 33
	v_writelane_b32 v255, s34, 34
	v_writelane_b32 v255, s35, 35
	v_writelane_b32 v255, s36, 36
	v_writelane_b32 v255, s37, 37
	v_writelane_b32 v255, s38, 38
	v_writelane_b32 v255, s39, 39
	v_writelane_b32 v255, s40, 40
	v_writelane_b32 v255, s41, 41
	v_writelane_b32 v255, s42, 42
	v_writelane_b32 v255, s43, 43
	v_writelane_b32 v255, s44, 44
	v_writelane_b32 v255, s45, 45
	v_writelane_b32 v255, s46, 46
	v_writelane_b32 v255, s47, 47
	v_writelane_b32 v255, s48, 48
	v_writelane_b32 v255, s49, 49
	v_writelane_b32 v255, s50, 50
	v_writelane_b32 v255, s51, 51
	v_writelane_b32 v255, s52, 52
	v_writelane_b32 v255, s53, 53
	v_writelane_b32 v255, s54, 54
	v_writelane_b32 v255, s55, 55
	v_writelane_b32 v255, s56, 56
	v_writelane_b32 v255, s57, 57
	v_writelane_b32 v255, s58, 58
	v_writelane_b32 v255, s59, 59
	v_writelane_b32 v255, s60, 60
	v_writelane_b32 v255, s61, 61
	v_writelane_b32 v255, s62, 62
	v_writelane_b32 v255, s63, 63
	v_writelane_b32 v254, s64, 0
	v_writelane_b32 v254, s65, 1
	v_writelane_b32 v254, s66, 2
	v_writelane_b32 v254, s67, 3
	v_writelane_b32 v254, s68, 4
	v_writelane_b32 v254, s69, 5
	v_writelane_b32 v254, s70, 6
	v_writelane_b32 v254, s71, 7
	v_writelane_b32 v254, s72, 8
	v_writelane_b32 v254, s73, 9
	v_writelane_b32 v254, s74, 10
	v_writelane_b32 v254, s75, 11
	v_writelane_b32 v254, s76, 12
	v_writelane_b32 v254, s77, 13
	v_readlane_b32 s4, v246, 4
	v_readlane_b32 s5, v246, 5
	v_readlane_b32 s24, v244, 54
	v_readlane_b32 s25, v243, 8
	v_readlane_b32 s26, v243, 7
	s_sub_u32 s4, s4, 0xe8
	s_subb_u32 s5, s5, 0
	s_load_dwordx2 s[6:7], s[4:5], 0x58
	s_load_dwordx2 s[8:9], s[4:5], 0x60
	s_load_dwordx2 s[10:11], s[4:5], 0x68
	s_load_dwordx2 s[12:13], s[4:5], 0x70
	s_load_dwordx2 s[14:15], s[4:5], 0x78
	s_load_dwordx2 s[16:17], s[4:5], 0x88
	s_load_dwordx2 s[18:19], s[4:5], 0x90
	s_load_dwordx2 s[20:21], s[4:5], 0x98
	s_load_dwordx2 s[22:23], s[4:5], 0xe0
	s_cmp_gt_u32 s26, 11
	s_cselect_b32 s26, 1, 0
	s_xor_b32 s52, s26, 1
	v_lshrrev_b32_e32 v225, 6, v196
	s_nop 0
	v_readfirstlane_b32 s30, v225
	s_mov_b32 s40, 0x11111111
	s_mov_b32 s41, 0x11111111
	s_mov_b32 s42, 0x22222222
	s_mov_b32 s43, 0x22222222
	s_mov_b32 s44, 0x44444444
	s_mov_b32 s45, 0x44444444
	s_mov_b32 s46, 0x88888888
	s_mov_b32 s47, 0x88888888
	v_mov_b32_e32 v240, 0
	s_waitcnt lgkmcnt(0)
	s_add_u32 s32, s22, 0x14360000
	s_addc_u32 s33, s23, 0
	s_sub_u32 s34, s32, 0x3c000
	s_subb_u32 s35, s33, 0

; DI void scan_item(const Params& p, int l, bool ctx_out, int item, char* smem) {
;     ...
;     for (int i = 0; i < TC; ++i) {
;       const f32x4 w4 = nw4, kk4 = nkk4, b4 = nb4, k4 = nk4, r4 = nr4, v4 = nv4;
;       if (i + 1 < TC) {
;         const int i1 = i + 1;
;         nw4 = *(const f32x4*)(ops + (i1 * 4 + 0) * 64 + 4 * kg);
;         nkk4 = *(const f32x4*)(ops + (i1 * 4 + 1) * 64 + 4 * kg);
;         nb4 = *(const f32x4*)(ops + (i1 * 4 + 2) * 64 + 4 * kg);
;         nk4 = *(const f32x4*)(ops + (i1 * 4 + 3) * 64 + 4 * kg);
;         nr4 = *(const f32x4*)(zs + (i1 * 3 + 0) * 64 + 4 * kg);
;         nv4 = *(const f32x4*)(zs + (i1 * 3 + 2) * 64 + 16 * w + 4 * rg);
;       }
;       float sk[4], y[4];
; #pragma unroll
;       for (int a = 0; a < 4; ++a) {
;         sk[a] = S[a][0] * kk4[0] + S[a][1] * kk4[1] + S[a][2] * kk4[2] + S[a][3] * kk4[3];
;         if (dir == 1) y[a] = S[a][0] * r4[0] + S[a][1] * r4[1] + S[a][2] * r4[2] + S[a][3] * r4[3];
;       }
; #pragma unroll
;       for (int a = 0; a < 4; ++a) sk[a] = allred16(sk[a]);
; #pragma unroll
;       for (int a = 0; a < 4; ++a)
; #pragma unroll
;         for (int j = 0; j < 4; ++j) S[a][j] = S[a][j] * w4[j] + (v4[a] * k4[j] - sk[a] * b4[j]);
;       if (dir == 0) {
; #pragma unroll
;         for (int a = 0; a < 4; ++a) y[a] = S[a][0] * r4[0] + S[a][1] * r4[1] + S[a][2] * r4[2] + S[a][3] * r4[3];
;       }
.Lscan_nobonus:
	s_cmp_eq_u32 s27, 1
	s_cbranch_scc1 .Lscan_steps_d1
	s_mov_b32 s53, 0
	ds_read_b128 v[72:75], v249 offset:1792
	ds_read_b128 v[76:79], v249 offset:1808
	ds_read_b128 v[88:91], v249 offset:2304
	ds_read_b128 v[92:95], v249 offset:2320
.Lscan_step_loop0:
	ds_read_b128 v[96:99], v249 offset:2560
	ds_read_b128 v[100:103], v249 offset:2576
	ds_read_b128 v[80:83], v249 offset:2048
	ds_read_b128 v[84:87], v249 offset:2064
	ds_read_b64 v[104:105], v250 offset:1536
	s_waitcnt lgkmcnt(9)
	s_add_i32 s53, s53, 1
	v_pk_mul_f32 v[122:123], v[6:7], v[30:31] op_sel_hi:[1,0]
	v_pk_mul_f32 v[126:127], v[8:9], v[30:31] op_sel:[0,1] op_sel_hi:[1,1]
	v_pk_fma_f32 v[122:123], v[10:11], v[32:33], v[122:123] op_sel_hi:[1,0,1]
	v_pk_fma_f32 v[126:127], v[12:13], v[32:33], v[126:127] op_sel:[0,1,0] op_sel_hi:[1,1,1]
	v_pk_fma_f32 v[122:123], v[14:15], v[34:35], v[122:123] op_sel_hi:[1,0,1]
	v_pk_fma_f32 v[126:127], v[16:17], v[34:35], v[126:127] op_sel:[0,1,0] op_sel_hi:[1,1,1]
	v_pk_fma_f32 v[122:123], v[18:19], v[36:37], v[122:123] op_sel_hi:[1,0,1]
	v_pk_fma_f32 v[126:127], v[20:21], v[36:37], v[126:127] op_sel:[0,1,0] op_sel_hi:[1,1,1]
	v_pk_add_f32 v[122:123], v[122:123], v[126:127]
	v_pk_fma_f32 v[6:7], v[62:63], v[46:47], v[6:7] op_sel_hi:[1,0,1]
	v_pk_fma_f32 v[8:9], v[62:63], v[46:47], v[8:9] op_sel:[0,1,0] op_sel_hi:[1,1,1]
	v_add_f32_dpp v122, v122, v122 quad_perm:[1,0,3,2] row_mask:0xf bank_mask:0xf bound_ctrl:1
	v_add_f32_dpp v123, v123, v123 quad_perm:[1,0,3,2] row_mask:0xf bank_mask:0xf bound_ctrl:1
	v_pk_fma_f32 v[10:11], v[62:63], v[48:49], v[10:11] op_sel_hi:[1,0,1]
	v_add_f32_dpp v122, v122, v122 quad_perm:[2,3,0,1] row_mask:0xf bank_mask:0xf bound_ctrl:1
	v_add_f32_dpp v123, v123, v123 quad_perm:[2,3,0,1] row_mask:0xf bank_mask:0xf bound_ctrl:1
	v_pk_fma_f32 v[12:13], v[62:63], v[48:49], v[12:13] op_sel:[0,1,0] op_sel_hi:[1,1,1]
	v_add_f32_dpp v122, v122, v122 row_half_mirror row_mask:0xf bank_mask:0xf bound_ctrl:1
	v_add_f32_dpp v123, v123, v123 row_half_mirror row_mask:0xf bank_mask:0xf bound_ctrl:1
	v_pk_fma_f32 v[14:15], v[62:63], v[50:51], v[14:15] op_sel_hi:[1,0,1]
	v_pk_fma_f32 v[16:17], v[62:63], v[50:51], v[16:17] op_sel:[0,1,0] op_sel_hi:[1,1,1]
	v_pk_fma_f32 v[18:19], v[62:63], v[52:53], v[18:19] op_sel_hi:[1,0,1]
	v_pk_fma_f32 v[20:21], v[62:63], v[52:53], v[20:21] op_sel:[0,1,0] op_sel_hi:[1,1,1]
	v_pk_fma_f32 v[6:7], v[122:123], v[38:39], v[6:7] op_sel_hi:[1,0,1] neg_lo:[1,0,0] neg_hi:[1,0,0]
	v_pk_fma_f32 v[8:9], v[122:123], v[38:39], v[8:9] op_sel:[0,1,0] op_sel_hi:[1,1,1] neg_lo:[1,0,0] neg_hi:[1,0,0]
	v_pk_mul_f32 v[124:125], v[6:7], v[54:55] op_sel_hi:[1,0]
	v_pk_fma_f32 v[10:11], v[122:123], v[40:41], v[10:11] op_sel_hi:[1,0,1] neg_lo:[1,0,0] neg_hi:[1,0,0]
	v_pk_mul_f32 v[128:129], v[8:9], v[54:55] op_sel:[0,1] op_sel_hi:[1,1]
	v_pk_fma_f32 v[12:13], v[122:123], v[40:41], v[12:13] op_sel:[0,1,0] op_sel_hi:[1,1,1] neg_lo:[1,0,0] neg_hi:[1,0,0]
	v_pk_fma_f32 v[124:125], v[10:11], v[56:57], v[124:125] op_sel_hi:[1,0,1]
	v_pk_fma_f32 v[14:15], v[122:123], v[42:43], v[14:15] op_sel_hi:[1,0,1] neg_lo:[1,0,0] neg_hi:[1,0,0]
	v_pk_fma_f32 v[128:129], v[12:13], v[56:57], v[128:129] op_sel:[0,1,0] op_sel_hi:[1,1,1]
	v_pk_fma_f32 v[16:17], v[122:123], v[42:43], v[16:17] op_sel:[0,1,0] op_sel_hi:[1,1,1] neg_lo:[1,0,0] neg_hi:[1,0,0]
	v_pk_fma_f32 v[124:125], v[14:15], v[58:59], v[124:125] op_sel_hi:[1,0,1]
	v_pk_fma_f32 v[18:19], v[122:123], v[44:45], v[18:19] op_sel_hi:[1,0,1] neg_lo:[1,0,0] neg_hi:[1,0,0]
	v_pk_fma_f32 v[128:129], v[16:17], v[58:59], v[128:129] op_sel:[0,1,0] op_sel_hi:[1,1,1]
	v_pk_fma_f32 v[20:21], v[122:123], v[44:45], v[20:21] op_sel:[0,1,0] op_sel_hi:[1,1,1] neg_lo:[1,0,0] neg_hi:[1,0,0]
	v_pk_fma_f32 v[124:125], v[18:19], v[60:61], v[124:125] op_sel_hi:[1,0,1]
	v_pk_fma_f32 v[128:129], v[20:21], v[60:61], v[128:129] op_sel:[0,1,0] op_sel_hi:[1,1,1]
	v_pk_add_f32 v[124:125], v[124:125], v[128:129]
	ds_read_b128 v[30:33], v249 offset:3328
	ds_read_b128 v[34:37], v249 offset:3344
	v_add_f32_dpp v124, v124, v124 quad_perm:[1,0,3,2] row_mask:0xf bank_mask:0xf bound_ctrl:1
	v_add_f32_dpp v125, v125, v125 quad_perm:[1,0,3,2] row_mask:0xf bank_mask:0xf bound_ctrl:1
	ds_read_b128 v[46:49], v249 offset:3840
	v_add_f32_dpp v124, v124, v124 quad_perm:[2,3,0,1] row_mask:0xf bank_mask:0xf bound_ctrl:1
	v_add_f32_dpp v125, v125, v125 quad_perm:[2,3,0,1] row_mask:0xf bank_mask:0xf bound_ctrl:1
	ds_read_b128 v[50:53], v249 offset:3856
	v_add_f32_dpp v124, v124, v124 row_half_mirror row_mask:0xf bank_mask:0xf bound_ctrl:1
	v_add_f32_dpp v125, v125, v125 row_half_mirror row_mask:0xf bank_mask:0xf bound_ctrl:1
	v_cvt_pk_bf16_f32 v247, v124, v125
	ds_write_b32 v251, v247 offset:0
	ds_read_b128 v[54:57], v249 offset:4096
	ds_read_b128 v[58:61], v249 offset:4112
	ds_read_b128 v[38:41], v249 offset:3584
	ds_read_b128 v[42:45], v249 offset:3600
	ds_read_b64 v[62:63], v250 offset:3072
	s_waitcnt lgkmcnt(9)
; DI unsigned pack2(float a, float b) { f32x2_t v = {a, b}; bf16x2_t r = __builtin_convertvector(v, bf16x2_t); return __builtin_bit_cast(unsigned, r); }
; DI void scan_item(const Params& p, int l, bool ctx_out, int item, char* smem) {
;     ...
;       float sk[4], y[4];
; #pragma unroll
;       for (int a = 0; a < 4; ++a) {
;         sk[a] = S[a][0] * kk4[0] + S[a][1] * kk4[1] + S[a][2] * kk4[2] + S[a][3] * kk4[3];
;         if (dir == 1) y[a] = S[a][0] * r4[0] + S[a][1] * r4[1] + S[a][2] * r4[2] + S[a][3] * r4[3];
;       }
; #pragma unroll
;       for (int a = 0; a < 4; ++a) sk[a] = allred16(sk[a]);
; #pragma unroll
;       for (int a = 0; a < 4; ++a)
; #pragma unroll
;         for (int j = 0; j < 4; ++j) S[a][j] = S[a][j] * w4[j] + (v4[a] * k4[j] - sk[a] * b4[j]);
;       if (dir == 0) {
; #pragma unroll
;         for (int a = 0; a < 4; ++a) y[a] = S[a][0] * r4[0] + S[a][1] * r4[1] + S[a][2] * r4[2] + S[a][3] * r4[3];
;       }
;       if (emit) {
;         float bo = r4[0] * k4[0] * rk4[0] + r4[1] * k4[1] * rk4[1] + r4[2] * k4[2] * rk4[2] + r4[3] * k4[3] * rk4[3];
;         bo = allred16(bo);
; #pragma unroll
;         for (int a = 0; a < 4; ++a) y[a] = allred16(y[a]);
;         if (kg == 0) {
;           const int sidx = c0 + i;
;           const int row = rbase + (dir == 0 ? sidx : n - 1 - sidx);
;           *(u32x2*)(YD + (size_t)row * 512 + h * 64 + 16 * w + 4 * rg) = mk2(pack2(y[0], y[1]), pack2(y[2], y[3]));
	s_cmp_lt_u32 s53, 8
	v_pk_mul_f32 v[122:123], v[6:7], v[72:73] op_sel_hi:[1,0]
	v_pk_mul_f32 v[126:127], v[8:9], v[72:73] op_sel:[0,1] op_sel_hi:[1,1]
	v_pk_fma_f32 v[122:123], v[10:11], v[74:75], v[122:123] op_sel_hi:[1,0,1]
	v_pk_fma_f32 v[126:127], v[12:13], v[74:75], v[126:127] op_sel:[0,1,0] op_sel_hi:[1,1,1]
	v_pk_fma_f32 v[122:123], v[14:15], v[76:77], v[122:123] op_sel_hi:[1,0,1]
	v_pk_fma_f32 v[126:127], v[16:17], v[76:77], v[126:127] op_sel:[0,1,0] op_sel_hi:[1,1,1]
	v_pk_fma_f32 v[122:123], v[18:19], v[78:79], v[122:123] op_sel_hi:[1,0,1]
	v_pk_fma_f32 v[126:127], v[20:21], v[78:79], v[126:127] op_sel:[0,1,0] op_sel_hi:[1,1,1]
	v_pk_add_f32 v[122:123], v[122:123], v[126:127]
	v_pk_fma_f32 v[6:7], v[104:105], v[88:89], v[6:7] op_sel_hi:[1,0,1]
	v_pk_fma_f32 v[8:9], v[104:105], v[88:89], v[8:9] op_sel:[0,1,0] op_sel_hi:[1,1,1]
	v_add_f32_dpp v122, v122, v122 quad_perm:[1,0,3,2] row_mask:0xf bank_mask:0xf bound_ctrl:1
	v_add_f32_dpp v123, v123, v123 quad_perm:[1,0,3,2] row_mask:0xf bank_mask:0xf bound_ctrl:1
	v_pk_fma_f32 v[10:11], v[104:105], v[90:91], v[10:11] op_sel_hi:[1,0,1]
	v_add_f32_dpp v122, v122, v122 quad_perm:[2,3,0,1] row_mask:0xf bank_mask:0xf bound_ctrl:1
	v_add_f32_dpp v123, v123, v123 quad_perm:[2,3,0,1] row_mask:0xf bank_mask:0xf bound_ctrl:1
	v_pk_fma_f32 v[12:13], v[104:105], v[90:91], v[12:13] op_sel:[0,1,0] op_sel_hi:[1,1,1]
	v_add_f32_dpp v122, v122, v122 row_half_mirror row_mask:0xf bank_mask:0xf bound_ctrl:1
	v_add_f32_dpp v123, v123, v123 row_half_mirror row_mask:0xf bank_mask:0xf bound_ctrl:1
	v_pk_fma_f32 v[14:15], v[104:105], v[92:93], v[14:15] op_sel_hi:[1,0,1]
	v_pk_fma_f32 v[16:17], v[104:105], v[92:93], v[16:17] op_sel:[0,1,0] op_sel_hi:[1,1,1]
	v_pk_fma_f32 v[18:19], v[104:105], v[94:95], v[18:19] op_sel_hi:[1,0,1]
	v_pk_fma_f32 v[20:21], v[104:105], v[94:95], v[20:21] op_sel:[0,1,0] op_sel_hi:[1,1,1]
	v_pk_fma_f32 v[6:7], v[122:123], v[80:81], v[6:7] op_sel_hi:[1,0,1] neg_lo:[1,0,0] neg_hi:[1,0,0]
	v_pk_fma_f32 v[8:9], v[122:123], v[80:81], v[8:9] op_sel:[0,1,0] op_sel_hi:[1,1,1] neg_lo:[1,0,0] neg_hi:[1,0,0]
	v_pk_mul_f32 v[124:125], v[6:7], v[96:97] op_sel_hi:[1,0]
	v_pk_fma_f32 v[10:11], v[122:123], v[82:83], v[10:11] op_sel_hi:[1,0,1] neg_lo:[1,0,0] neg_hi:[1,0,0]
	v_pk_mul_f32 v[128:129], v[8:9], v[96:97] op_sel:[0,1] op_sel_hi:[1,1]
	v_pk_fma_f32 v[12:13], v[122:123], v[82:83], v[12:13] op_sel:[0,1,0] op_sel_hi:[1,1,1] neg_lo:[1,0,0] neg_hi:[1,0,0]
	v_pk_fma_f32 v[124:125], v[10:11], v[98:99], v[124:125] op_sel_hi:[1,0,1]
	v_pk_fma_f32 v[14:15], v[122:123], v[84:85], v[14:15] op_sel_hi:[1,0,1] neg_lo:[1,0,0] neg_hi:[1,0,0]
	v_pk_fma_f32 v[128:129], v[12:13], v[98:99], v[128:129] op_sel:[0,1,0] op_sel_hi:[1,1,1]
	v_pk_fma_f32 v[16:17], v[122:123], v[84:85], v[16:17] op_sel:[0,1,0] op_sel_hi:[1,1,1] neg_lo:[1,0,0] neg_hi:[1,0,0]
	v_pk_fma_f32 v[124:125], v[14:15], v[100:101], v[124:125] op_sel_hi:[1,0,1]
	v_pk_fma_f32 v[18:19], v[122:123], v[86:87], v[18:19] op_sel_hi:[1,0,1] neg_lo:[1,0,0] neg_hi:[1,0,0]
	v_pk_fma_f32 v[128:129], v[16:17], v[100:101], v[128:129] op_sel:[0,1,0] op_sel_hi:[1,1,1]
	v_pk_fma_f32 v[20:21], v[122:123], v[86:87], v[20:21] op_sel:[0,1,0] op_sel_hi:[1,1,1] neg_lo:[1,0,0] neg_hi:[1,0,0]
	v_pk_fma_f32 v[124:125], v[18:19], v[102:103], v[124:125] op_sel_hi:[1,0,1]
	v_pk_fma_f32 v[128:129], v[20:21], v[102:103], v[128:129] op_sel:[0,1,0] op_sel_hi:[1,1,1]
	v_pk_add_f32 v[124:125], v[124:125], v[128:129]
	ds_read_b128 v[72:75], v249 offset:4864
	ds_read_b128 v[76:79], v249 offset:4880
	v_add_f32_dpp v124, v124, v124 quad_perm:[1,0,3,2] row_mask:0xf bank_mask:0xf bound_ctrl:1
	v_add_f32_dpp v125, v125, v125 quad_perm:[1,0,3,2] row_mask:0xf bank_mask:0xf bound_ctrl:1
	ds_read_b128 v[88:91], v249 offset:5376
	v_add_f32_dpp v124, v124, v124 quad_perm:[2,3,0,1] row_mask:0xf bank_mask:0xf bound_ctrl:1
	v_add_f32_dpp v125, v125, v125 quad_perm:[2,3,0,1] row_mask:0xf bank_mask:0xf bound_ctrl:1
	ds_read_b128 v[92:95], v249 offset:5392
	v_add_f32_dpp v124, v124, v124 row_half_mirror row_mask:0xf bank_mask:0xf bound_ctrl:1
	v_add_f32_dpp v125, v125, v125 row_half_mirror row_mask:0xf bank_mask:0xf bound_ctrl:1
	v_cvt_pk_bf16_f32 v247, v124, v125
	ds_write_b32 v251, v247 offset:128
	v_add_u32_e32 v249, 3072, v249
	v_add_u32_e32 v250, 3072, v250
	v_add_u32_e32 v251, 256, v251
	s_cbranch_scc1 .Lscan_step_loop0
	s_branch .Lscan_flush
	s_nop 0
	s_nop 0
	s_nop 0
	s_nop 0
	s_nop 0
	s_nop 0
	s_nop 0
	s_nop 0
	s_nop 0
	s_nop 0
	s_nop 0
	s_nop 0
	s_nop 0
	s_nop 0
	s_nop 0

; DI void scan_item(const Params& p, int l, bool ctx_out, int item, char* smem) {
;     ...
;     for (int i = 0; i < TC; ++i) {
;       const f32x4 w4 = nw4, kk4 = nkk4, b4 = nb4, k4 = nk4, r4 = nr4, v4 = nv4;
;       if (i + 1 < TC) {
;         const int i1 = i + 1;
;         nw4 = *(const f32x4*)(ops + (i1 * 4 + 0) * 64 + 4 * kg);
;         nkk4 = *(const f32x4*)(ops + (i1 * 4 + 1) * 64 + 4 * kg);
;         nb4 = *(const f32x4*)(ops + (i1 * 4 + 2) * 64 + 4 * kg);
;         nk4 = *(const f32x4*)(ops + (i1 * 4 + 3) * 64 + 4 * kg);
;         nr4 = *(const f32x4*)(zs + (i1 * 3 + 0) * 64 + 4 * kg);
;         nv4 = *(const f32x4*)(zs + (i1 * 3 + 2) * 64 + 16 * w + 4 * rg);
;       }
;       float sk[4], y[4];
; #pragma unroll
;       for (int a = 0; a < 4; ++a) {
;         sk[a] = S[a][0] * kk4[0] + S[a][1] * kk4[1] + S[a][2] * kk4[2] + S[a][3] * kk4[3];
;         if (dir == 1) y[a] = S[a][0] * r4[0] + S[a][1] * r4[1] + S[a][2] * r4[2] + S[a][3] * r4[3];
;       }
; #pragma unroll
;       for (int a = 0; a < 4; ++a) sk[a] = allred16(sk[a]);
; #pragma unroll
;       for (int a = 0; a < 4; ++a)
; #pragma unroll
;         for (int j = 0; j < 4; ++j) S[a][j] = S[a][j] * w4[j] + (v4[a] * k4[j] - sk[a] * b4[j]);
.Lscan_step_loop1:
	ds_read_b128 v[72:75], v249 offset:1792
	ds_read_b128 v[76:79], v249 offset:1808
	ds_read_b128 v[88:91], v249 offset:2304
	ds_read_b128 v[92:95], v249 offset:2320
	ds_read_b128 v[96:99], v249 offset:2560
	ds_read_b128 v[100:103], v249 offset:2576
	ds_read_b128 v[80:83], v249 offset:2048
	ds_read_b128 v[84:87], v249 offset:2064
	ds_read_b64 v[104:105], v250 offset:1536
	s_waitcnt lgkmcnt(9)
	s_add_i32 s53, s53, 1
	v_pk_mul_f32 v[122:123], v[6:7], v[30:31] op_sel_hi:[1,0]
	v_pk_mul_f32 v[124:125], v[6:7], v[54:55] op_sel_hi:[1,0]
	v_pk_mul_f32 v[126:127], v[8:9], v[30:31] op_sel:[0,1] op_sel_hi:[1,1]
	v_pk_mul_f32 v[128:129], v[8:9], v[54:55] op_sel:[0,1] op_sel_hi:[1,1]
	v_pk_fma_f32 v[122:123], v[10:11], v[32:33], v[122:123] op_sel_hi:[1,0,1]
	v_pk_fma_f32 v[124:125], v[10:11], v[56:57], v[124:125] op_sel_hi:[1,0,1]
	v_pk_fma_f32 v[126:127], v[12:13], v[32:33], v[126:127] op_sel:[0,1,0] op_sel_hi:[1,1,1]
	v_pk_fma_f32 v[128:129], v[12:13], v[56:57], v[128:129] op_sel:[0,1,0] op_sel_hi:[1,1,1]
	v_pk_fma_f32 v[122:123], v[14:15], v[34:35], v[122:123] op_sel_hi:[1,0,1]
	v_pk_fma_f32 v[124:125], v[14:15], v[58:59], v[124:125] op_sel_hi:[1,0,1]
	v_pk_fma_f32 v[126:127], v[16:17], v[34:35], v[126:127] op_sel:[0,1,0] op_sel_hi:[1,1,1]
	v_pk_fma_f32 v[128:129], v[16:17], v[58:59], v[128:129] op_sel:[0,1,0] op_sel_hi:[1,1,1]
	v_pk_fma_f32 v[122:123], v[18:19], v[36:37], v[122:123] op_sel_hi:[1,0,1]
	v_pk_fma_f32 v[124:125], v[18:19], v[60:61], v[124:125] op_sel_hi:[1,0,1]
	v_pk_fma_f32 v[126:127], v[20:21], v[36:37], v[126:127] op_sel:[0,1,0] op_sel_hi:[1,1,1]
	v_pk_fma_f32 v[128:129], v[20:21], v[60:61], v[128:129] op_sel:[0,1,0] op_sel_hi:[1,1,1]
	v_pk_add_f32 v[122:123], v[122:123], v[126:127]
	v_pk_add_f32 v[124:125], v[124:125], v[128:129]
	v_pk_fma_f32 v[6:7], v[62:63], v[46:47], v[6:7] op_sel_hi:[1,0,1]
	v_add_f32_dpp v122, v122, v122 quad_perm:[1,0,3,2] row_mask:0xf bank_mask:0xf bound_ctrl:1
	v_add_f32_dpp v123, v123, v123 quad_perm:[1,0,3,2] row_mask:0xf bank_mask:0xf bound_ctrl:1
	v_add_f32_dpp v124, v124, v124 quad_perm:[1,0,3,2] row_mask:0xf bank_mask:0xf bound_ctrl:1
	v_add_f32_dpp v125, v125, v125 quad_perm:[1,0,3,2] row_mask:0xf bank_mask:0xf bound_ctrl:1
	v_add_f32_dpp v122, v122, v122 quad_perm:[2,3,0,1] row_mask:0xf bank_mask:0xf bound_ctrl:1
	v_add_f32_dpp v123, v123, v123 quad_perm:[2,3,0,1] row_mask:0xf bank_mask:0xf bound_ctrl:1
	v_add_f32_dpp v124, v124, v124 quad_perm:[2,3,0,1] row_mask:0xf bank_mask:0xf bound_ctrl:1
	v_add_f32_dpp v125, v125, v125 quad_perm:[2,3,0,1] row_mask:0xf bank_mask:0xf bound_ctrl:1
	v_add_f32_dpp v122, v122, v122 row_half_mirror row_mask:0xf bank_mask:0xf bound_ctrl:1
	v_add_f32_dpp v123, v123, v123 row_half_mirror row_mask:0xf bank_mask:0xf bound_ctrl:1
	v_add_f32_dpp v124, v124, v124 row_half_mirror row_mask:0xf bank_mask:0xf bound_ctrl:1
	v_add_f32_dpp v125, v125, v125 row_half_mirror row_mask:0xf bank_mask:0xf bound_ctrl:1
	v_pk_fma_f32 v[8:9], v[62:63], v[46:47], v[8:9] op_sel:[0,1,0] op_sel_hi:[1,1,1]
	v_pk_fma_f32 v[10:11], v[62:63], v[48:49], v[10:11] op_sel_hi:[1,0,1]
	v_pk_fma_f32 v[12:13], v[62:63], v[48:49], v[12:13] op_sel:[0,1,0] op_sel_hi:[1,1,1]
	v_pk_fma_f32 v[14:15], v[62:63], v[50:51], v[14:15] op_sel_hi:[1,0,1]
	v_pk_fma_f32 v[16:17], v[62:63], v[50:51], v[16:17] op_sel:[0,1,0] op_sel_hi:[1,1,1]
	v_pk_fma_f32 v[18:19], v[62:63], v[52:53], v[18:19] op_sel_hi:[1,0,1]
	v_pk_fma_f32 v[20:21], v[62:63], v[52:53], v[20:21] op_sel:[0,1,0] op_sel_hi:[1,1,1]
	v_pk_fma_f32 v[6:7], v[122:123], v[38:39], v[6:7] op_sel_hi:[1,0,1] neg_lo:[1,0,0] neg_hi:[1,0,0]
	v_pk_fma_f32 v[8:9], v[122:123], v[38:39], v[8:9] op_sel:[0,1,0] op_sel_hi:[1,1,1] neg_lo:[1,0,0] neg_hi:[1,0,0]
	v_pk_fma_f32 v[10:11], v[122:123], v[40:41], v[10:11] op_sel_hi:[1,0,1] neg_lo:[1,0,0] neg_hi:[1,0,0]
	v_pk_fma_f32 v[12:13], v[122:123], v[40:41], v[12:13] op_sel:[0,1,0] op_sel_hi:[1,1,1] neg_lo:[1,0,0] neg_hi:[1,0,0]
	v_pk_fma_f32 v[14:15], v[122:123], v[42:43], v[14:15] op_sel_hi:[1,0,1] neg_lo:[1,0,0] neg_hi:[1,0,0]
	v_pk_fma_f32 v[16:17], v[122:123], v[42:43], v[16:17] op_sel:[0,1,0] op_sel_hi:[1,1,1] neg_lo:[1,0,0] neg_hi:[1,0,0]
	v_pk_fma_f32 v[18:19], v[122:123], v[44:45], v[18:19] op_sel_hi:[1,0,1] neg_lo:[1,0,0] neg_hi:[1,0,0]
	v_pk_fma_f32 v[20:21], v[122:123], v[44:45], v[20:21] op_sel:[0,1,0] op_sel_hi:[1,1,1] neg_lo:[1,0,0] neg_hi:[1,0,0]
	v_cvt_pk_bf16_f32 v247, v124, v125
	ds_write_b32 v251, v247 offset:0
	ds_read_b128 v[30:33], v249 offset:3328
	ds_read_b128 v[34:37], v249 offset:3344
	ds_read_b128 v[46:49], v249 offset:3840
	ds_read_b128 v[50:53], v249 offset:3856
	ds_read_b128 v[54:57], v249 offset:4096
	ds_read_b128 v[58:61], v249 offset:4112
	ds_read_b128 v[38:41], v249 offset:3584
	ds_read_b128 v[42:45], v249 offset:3600
	ds_read_b64 v[62:63], v250 offset:3072
	s_waitcnt lgkmcnt(9)
; DI void scan_item(const Params& p, int l, bool ctx_out, int item, char* smem) {
;     ...
;     for (int i = 0; i < TC; ++i) {
;       const f32x4 w4 = nw4, kk4 = nkk4, b4 = nb4, k4 = nk4, r4 = nr4, v4 = nv4;
;       if (i + 1 < TC) {
;         const int i1 = i + 1;
;         nw4 = *(const f32x4*)(ops + (i1 * 4 + 0) * 64 + 4 * kg);
;         nkk4 = *(const f32x4*)(ops + (i1 * 4 + 1) * 64 + 4 * kg);
;         nb4 = *(const f32x4*)(ops + (i1 * 4 + 2) * 64 + 4 * kg);
;         nk4 = *(const f32x4*)(ops + (i1 * 4 + 3) * 64 + 4 * kg);
;         nr4 = *(const f32x4*)(zs + (i1 * 3 + 0) * 64 + 4 * kg);
;         nv4 = *(const f32x4*)(zs + (i1 * 3 + 2) * 64 + 16 * w + 4 * rg);
;       }
;       float sk[4], y[4];
; #pragma unroll
;       for (int a = 0; a < 4; ++a) {
;         sk[a] = S[a][0] * kk4[0] + S[a][1] * kk4[1] + S[a][2] * kk4[2] + S[a][3] * kk4[3];
;         if (dir == 1) y[a] = S[a][0] * r4[0] + S[a][1] * r4[1] + S[a][2] * r4[2] + S[a][3] * r4[3];
;       }
; #pragma unroll
;       for (int a = 0; a < 4; ++a) sk[a] = allred16(sk[a]);
; #pragma unroll
;       for (int a = 0; a < 4; ++a)
; #pragma unroll
;         for (int j = 0; j < 4; ++j) S[a][j] = S[a][j] * w4[j] + (v4[a] * k4[j] - sk[a] * b4[j]);
	s_cmp_lt_u32 s53, 8
	v_pk_mul_f32 v[122:123], v[6:7], v[72:73] op_sel_hi:[1,0]
	v_pk_mul_f32 v[124:125], v[6:7], v[96:97] op_sel_hi:[1,0]
	v_pk_mul_f32 v[126:127], v[8:9], v[72:73] op_sel:[0,1] op_sel_hi:[1,1]
	v_pk_mul_f32 v[128:129], v[8:9], v[96:97] op_sel:[0,1] op_sel_hi:[1,1]
	v_pk_fma_f32 v[122:123], v[10:11], v[74:75], v[122:123] op_sel_hi:[1,0,1]
	v_pk_fma_f32 v[124:125], v[10:11], v[98:99], v[124:125] op_sel_hi:[1,0,1]
	v_pk_fma_f32 v[126:127], v[12:13], v[74:75], v[126:127] op_sel:[0,1,0] op_sel_hi:[1,1,1]
	v_pk_fma_f32 v[128:129], v[12:13], v[98:99], v[128:129] op_sel:[0,1,0] op_sel_hi:[1,1,1]
	v_pk_fma_f32 v[122:123], v[14:15], v[76:77], v[122:123] op_sel_hi:[1,0,1]
	v_pk_fma_f32 v[124:125], v[14:15], v[100:101], v[124:125] op_sel_hi:[1,0,1]
	v_pk_fma_f32 v[126:127], v[16:17], v[76:77], v[126:127] op_sel:[0,1,0] op_sel_hi:[1,1,1]
	v_pk_fma_f32 v[128:129], v[16:17], v[100:101], v[128:129] op_sel:[0,1,0] op_sel_hi:[1,1,1]
	v_pk_fma_f32 v[122:123], v[18:19], v[78:79], v[122:123] op_sel_hi:[1,0,1]
	v_pk_fma_f32 v[124:125], v[18:19], v[102:103], v[124:125] op_sel_hi:[1,0,1]
	v_pk_fma_f32 v[126:127], v[20:21], v[78:79], v[126:127] op_sel:[0,1,0] op_sel_hi:[1,1,1]
	v_pk_fma_f32 v[128:129], v[20:21], v[102:103], v[128:129] op_sel:[0,1,0] op_sel_hi:[1,1,1]
	v_pk_add_f32 v[122:123], v[122:123], v[126:127]
	v_pk_add_f32 v[124:125], v[124:125], v[128:129]
	v_pk_fma_f32 v[6:7], v[104:105], v[88:89], v[6:7] op_sel_hi:[1,0,1]
	v_add_f32_dpp v122, v122, v122 quad_perm:[1,0,3,2] row_mask:0xf bank_mask:0xf bound_ctrl:1
	v_add_f32_dpp v123, v123, v123 quad_perm:[1,0,3,2] row_mask:0xf bank_mask:0xf bound_ctrl:1
	v_add_f32_dpp v124, v124, v124 quad_perm:[1,0,3,2] row_mask:0xf bank_mask:0xf bound_ctrl:1
	v_add_f32_dpp v125, v125, v125 quad_perm:[1,0,3,2] row_mask:0xf bank_mask:0xf bound_ctrl:1
	v_add_f32_dpp v122, v122, v122 quad_perm:[2,3,0,1] row_mask:0xf bank_mask:0xf bound_ctrl:1
	v_add_f32_dpp v123, v123, v123 quad_perm:[2,3,0,1] row_mask:0xf bank_mask:0xf bound_ctrl:1
	v_add_f32_dpp v124, v124, v124 quad_perm:[2,3,0,1] row_mask:0xf bank_mask:0xf bound_ctrl:1
	v_add_f32_dpp v125, v125, v125 quad_perm:[2,3,0,1] row_mask:0xf bank_mask:0xf bound_ctrl:1
	v_add_f32_dpp v122, v122, v122 row_half_mirror row_mask:0xf bank_mask:0xf bound_ctrl:1
	v_add_f32_dpp v123, v123, v123 row_half_mirror row_mask:0xf bank_mask:0xf bound_ctrl:1
	v_add_f32_dpp v124, v124, v124 row_half_mirror row_mask:0xf bank_mask:0xf bound_ctrl:1
	v_add_f32_dpp v125, v125, v125 row_half_mirror row_mask:0xf bank_mask:0xf bound_ctrl:1
	v_pk_fma_f32 v[8:9], v[104:105], v[88:89], v[8:9] op_sel:[0,1,0] op_sel_hi:[1,1,1]
	v_pk_fma_f32 v[10:11], v[104:105], v[90:91], v[10:11] op_sel_hi:[1,0,1]
	v_pk_fma_f32 v[12:13], v[104:105], v[90:91], v[12:13] op_sel:[0,1,0] op_sel_hi:[1,1,1]
	v_pk_fma_f32 v[14:15], v[104:105], v[92:93], v[14:15] op_sel_hi:[1,0,1]
	v_pk_fma_f32 v[16:17], v[104:105], v[92:93], v[16:17] op_sel:[0,1,0] op_sel_hi:[1,1,1]
	v_pk_fma_f32 v[18:19], v[104:105], v[94:95], v[18:19] op_sel_hi:[1,0,1]
	v_pk_fma_f32 v[20:21], v[104:105], v[94:95], v[20:21] op_sel:[0,1,0] op_sel_hi:[1,1,1]
	v_pk_fma_f32 v[6:7], v[122:123], v[80:81], v[6:7] op_sel_hi:[1,0,1] neg_lo:[1,0,0] neg_hi:[1,0,0]
	v_pk_fma_f32 v[8:9], v[122:123], v[80:81], v[8:9] op_sel:[0,1,0] op_sel_hi:[1,1,1] neg_lo:[1,0,0] neg_hi:[1,0,0]
	v_pk_fma_f32 v[10:11], v[122:123], v[82:83], v[10:11] op_sel_hi:[1,0,1] neg_lo:[1,0,0] neg_hi:[1,0,0]
	v_pk_fma_f32 v[12:13], v[122:123], v[82:83], v[12:13] op_sel:[0,1,0] op_sel_hi:[1,1,1] neg_lo:[1,0,0] neg_hi:[1,0,0]
	v_pk_fma_f32 v[14:15], v[122:123], v[84:85], v[14:15] op_sel_hi:[1,0,1] neg_lo:[1,0,0] neg_hi:[1,0,0]
	v_pk_fma_f32 v[16:17], v[122:123], v[84:85], v[16:17] op_sel:[0,1,0] op_sel_hi:[1,1,1] neg_lo:[1,0,0] neg_hi:[1,0,0]
	v_pk_fma_f32 v[18:19], v[122:123], v[86:87], v[18:19] op_sel_hi:[1,0,1] neg_lo:[1,0,0] neg_hi:[1,0,0]
	v_pk_fma_f32 v[20:21], v[122:123], v[86:87], v[20:21] op_sel:[0,1,0] op_sel_hi:[1,1,1] neg_lo:[1,0,0] neg_hi:[1,0,0]
	v_cvt_pk_bf16_f32 v247, v124, v125
	ds_write_b32 v251, v247 offset:128
	v_add_u32_e32 v249, 3072, v249
	v_add_u32_e32 v250, 3072, v250
	v_add_u32_e32 v251, 256, v251
	s_cbranch_scc1 .Lscan_step_loop1

; DI void scan_item(const Params& p, int l, bool ctx_out, int item, char* smem) {
;     ...
;     }
;     __syncthreads();
;   }
;     ...
; }
.Lscan_exit:
	v_readlane_b32 s0, v255, 0
	v_readlane_b32 s1, v255, 1
	v_readlane_b32 s2, v255, 2
	v_readlane_b32 s3, v255, 3
	v_readlane_b32 s4, v255, 4
	v_readlane_b32 s5, v255, 5
	v_readlane_b32 s6, v255, 6
	v_readlane_b32 s7, v255, 7
	v_readlane_b32 s8, v255, 8
	v_readlane_b32 s9, v255, 9
	v_readlane_b32 s10, v255, 10
	v_readlane_b32 s11, v255, 11
	v_readlane_b32 s12, v255, 12
	v_readlane_b32 s13, v255, 13
	v_readlane_b32 s14, v255, 14
	v_readlane_b32 s15, v255, 15
	v_readlane_b32 s16, v255, 16
	v_readlane_b32 s17, v255, 17
	v_readlane_b32 s18, v255, 18
	v_readlane_b32 s19, v255, 19
	v_readlane_b32 s20, v255, 20
	v_readlane_b32 s21, v255, 21
	v_readlane_b32 s22, v255, 22
	v_readlane_b32 s23, v255, 23
	v_readlane_b32 s24, v255, 24
	v_readlane_b32 s25, v255, 25
	v_readlane_b32 s26, v255, 26
	v_readlane_b32 s27, v255, 27
	v_readlane_b32 s28, v255, 28
	v_readlane_b32 s29, v255, 29
	v_readlane_b32 s30, v255, 30
	v_readlane_b32 s31, v255, 31
	v_readlane_b32 s32, v255, 32
	v_readlane_b32 s33, v255, 33
	v_readlane_b32 s34, v255, 34
	v_readlane_b32 s35, v255, 35
	v_readlane_b32 s36, v255, 36
	v_readlane_b32 s37, v255, 37
	v_readlane_b32 s38, v255, 38
	v_readlane_b32 s39, v255, 39
	v_readlane_b32 s40, v255, 40
	v_readlane_b32 s41, v255, 41
	v_readlane_b32 s42, v255, 42
	v_readlane_b32 s43, v255, 43
	v_readlane_b32 s44, v255, 44
	v_readlane_b32 s45, v255, 45
	v_readlane_b32 s46, v255, 46
	v_readlane_b32 s47, v255, 47
	v_readlane_b32 s48, v255, 48
	v_readlane_b32 s49, v255, 49
	v_readlane_b32 s50, v255, 50
	v_readlane_b32 s51, v255, 51
	v_readlane_b32 s52, v255, 52
	v_readlane_b32 s53, v255, 53
	v_readlane_b32 s54, v255, 54
	v_readlane_b32 s55, v255, 55
	v_readlane_b32 s56, v255, 56
	v_readlane_b32 s57, v255, 57
	v_readlane_b32 s58, v255, 58
	v_readlane_b32 s59, v255, 59
	v_readlane_b32 s60, v255, 60
	v_readlane_b32 s61, v255, 61
	v_readlane_b32 s62, v255, 62
	v_readlane_b32 s63, v255, 63
	v_readlane_b32 s64, v254, 0
	v_readlane_b32 s65, v254, 1
	v_readlane_b32 s66, v254, 2
	v_readlane_b32 s67, v254, 3
	v_readlane_b32 s68, v254, 4
	v_readlane_b32 s69, v254, 5
	v_readlane_b32 s70, v254, 6
	v_readlane_b32 s71, v254, 7
	v_readlane_b32 s72, v254, 8
	v_readlane_b32 s73, v254, 9
	v_readlane_b32 s74, v254, 10
	v_readlane_b32 s75, v254, 11
	v_readlane_b32 s76, v254, 12
	v_readlane_b32 s77, v254, 13
	.p2alignl 7, 3212836864
	s_nop 0
